# t1 + P5 loop: the 12 first x/proj loads issued before waiting on the row partial-sum loads (counted wait)
# baseline (speedup 1.0000x reference)
.LBB0_752:
	s_or_b64 exec, exec, s[4:5]
	v_lshl_add_u64 v[38:39], s[66:67], 0, v[92:93]
	v_add_co_u32_e32 v94, vcc, 0xe000000, v38
	v_addc_co_u32_e32 v95, vcc, 0, v39, vcc
	v_lshl_add_u64 v[34:35], s[16:17], 0, v[80:81]
	s_lshl_b64 s[20:21], s[2:3], 13
	v_lshl_add_u64 v[36:37], v[84:85], 0, s[20:21]
	global_load_dwordx4 v[120:123], v[34:35], off nt
	global_load_dwordx4 v[124:127], v[34:35], off offset:1024 nt
	global_load_dwordx4 v[128:131], v[36:37], off nt
	global_load_dwordx4 v[132:135], v[36:37], off offset:1024 nt
	global_load_dwordx4 v[76:79], v[34:35], off offset:2048 nt
	global_load_dwordx4 v[60:63], v[34:35], off offset:3072 nt
	global_load_dwordx4 v[72:75], v[36:37], off offset:2048 nt
	global_load_dwordx4 v[56:59], v[36:37], off offset:3072 nt
	global_load_dwordx2 v[136:137], v[94:95], off nt
	global_load_dwordx2 v[138:139], v[94:95], off offset:512 nt
	global_load_dwordx2 v[140:141], v[94:95], off offset:1024 nt
	global_load_dwordx2 v[110:111], v[94:95], off offset:1536 nt
	s_waitcnt vmcnt(12)
	ds_bpermute_b32 v38, v103, v33
	ds_bpermute_b32 v39, v103, v32
	s_waitcnt lgkmcnt(1)
	v_add_f32_e32 v33, v33, v38
	ds_bpermute_b32 v38, v105, v33
	v_add_co_u32_e32 v34, vcc, s23, v34
	s_waitcnt lgkmcnt(0)
	v_add_f32_e32 v33, v33, v38
	ds_bpermute_b32 v38, v114, v33
	s_lshl_b64 s[2:3], s[2:3], 12
	v_addc_co_u32_e32 v35, vcc, 0, v35, vcc
	v_lshl_add_u64 v[96:97], v[86:87], 0, s[2:3]
	s_waitcnt lgkmcnt(0)
	v_add_f32_e32 v33, v33, v38
	v_add_co_u32_e32 v98, vcc, s23, v36
	ds_bpermute_b32 v36, v115, v33
	global_load_dwordx2 v[142:143], v[96:97], off nt
	global_load_dwordx2 v[144:145], v[96:97], off offset:512 nt
	global_load_dwordx2 v[146:147], v[96:97], off offset:1024 nt
	global_load_dwordx2 v[112:113], v[96:97], off offset:1536 nt
	v_add_f32_e32 v32, v32, v39
	v_addc_co_u32_e32 v99, vcc, 0, v37, vcc
	ds_bpermute_b32 v37, v105, v32
	s_waitcnt lgkmcnt(1)
	v_add_f32_e32 v33, v33, v36
	ds_bpermute_b32 v36, v116, v33
	global_load_dwordx4 v[68:71], v[34:35], off nt
	global_load_dwordx4 v[52:55], v[34:35], off offset:1024 nt
	global_load_dwordx4 v[64:67], v[98:99], off nt
	global_load_dwordx4 v[48:51], v[98:99], off offset:1024 nt
	s_waitcnt lgkmcnt(1)
	v_add_f32_e32 v32, v32, v37
	ds_bpermute_b32 v37, v114, v32
	s_waitcnt lgkmcnt(1)
	v_add_f32_e32 v100, v33, v36
	ds_bpermute_b32 v101, v117, v100
	s_add_i32 s6, s6, s8
	v_lshl_add_u64 v[90:91], v[90:91], 0, s[14:15]
	s_waitcnt lgkmcnt(1)
	v_add_f32_e32 v102, v32, v37
	ds_bpermute_b32 v104, v115, v102
	global_load_dwordx4 v[44:47], v[34:35], off offset:2048 nt
	global_load_dwordx4 v[36:39], v[34:35], off offset:3072 nt
	global_load_dwordx4 v[40:43], v[98:99], off offset:2048 nt
	s_nop 0
	global_load_dwordx4 v[32:35], v[98:99], off offset:3072 nt
	s_waitcnt lgkmcnt(1)
	v_add_f32_e32 v98, v100, v101
	v_fmamk_f32 v98, v98, 0x3a000000, v118
	v_mul_f32_e32 v99, 0x4f800000, v98
	s_waitcnt lgkmcnt(0)
	v_add_f32_e32 v100, v102, v104
	v_cmp_gt_f32_e32 vcc, s7, v98
	ds_bpermute_b32 v101, v116, v100
	v_lshl_add_u64 v[92:93], v[92:93], 0, s[18:19]
	v_cndmask_b32_e32 v102, v98, v99, vcc
	v_sqrt_f32_e32 v104, v102
	global_load_dwordx2 v[148:149], v[94:95], off offset:2048 nt
	global_load_dwordx2 v[106:107], v[94:95], off offset:2560 nt
	global_load_dwordx2 v[98:99], v[94:95], off offset:3072 nt
	s_nop 0
	global_load_dwordx2 v[94:95], v[94:95], off offset:3584 nt
	s_waitcnt lgkmcnt(0)
	v_add_f32_e32 v152, v100, v101
	ds_bpermute_b32 v153, v117, v152
	v_add_u32_e32 v100, -1, v104
	v_fma_f32 v101, -v100, v104, v102
	v_cmp_ge_f32_e64 s[2:3], 0, v101
	v_add_u32_e32 v101, 1, v104
	s_waitcnt lgkmcnt(0)
	v_add_f32_e32 v152, v152, v153
	v_cndmask_b32_e64 v100, v104, v100, s[2:3]
	v_fma_f32 v104, -v101, v104, v102
	v_cmp_lt_f32_e64 s[2:3], 0, v104
	v_fmamk_f32 v152, v152, 0x3a000000, v118
	v_mul_f32_e32 v156, 0x4f800000, v152
	v_cndmask_b32_e64 v100, v100, v101, s[2:3]
	v_mul_f32_e32 v101, 0x37800000, v100
	v_cndmask_b32_e32 v100, v100, v101, vcc
	v_cmp_class_f32_e32 vcc, v102, v119
	s_nop 1
	v_cndmask_b32_e32 v102, v100, v102, vcc
	global_load_dwordx2 v[150:151], v[96:97], off offset:2048 nt
	global_load_dwordx2 v[108:109], v[96:97], off offset:2560 nt
	global_load_dwordx2 v[100:101], v[96:97], off offset:3072 nt
	s_nop 0
	global_load_dwordx2 v[96:97], v[96:97], off offset:3584 nt
	v_div_scale_f32 v104, s[2:3], v102, v102, 1.0
	v_rcp_f32_e32 v154, v104
	v_cmp_gt_f32_e64 s[2:3], s7, v152
	v_fma_f32 v153, -v104, v154, 1.0
	s_nop 0
	v_cndmask_b32_e64 v152, v152, v156, s[2:3]
	v_fmac_f32_e32 v154, v153, v154
	v_div_scale_f32 v153, vcc, 1.0, v102, 1.0
	v_sqrt_f32_e32 v156, v152
	v_mul_f32_e32 v155, v153, v154
	v_fma_f32 v157, -v104, v155, v153
	v_fmac_f32_e32 v155, v157, v154
	v_fma_f32 v104, -v104, v155, v153
	v_add_u32_e32 v153, -1, v156
	v_fma_f32 v157, -v153, v156, v152
	v_cmp_ge_f32_e64 s[4:5], 0, v157
	v_add_u32_e32 v157, 1, v156
	v_div_fmas_f32 v104, v104, v154, v155
	v_cndmask_b32_e64 v153, v156, v153, s[4:5]
	v_fma_f32 v156, -v157, v156, v152
	v_cmp_lt_f32_e64 s[4:5], 0, v156
	v_div_fixup_f32 v104, v104, v102, 1.0
	s_nop 0
	v_cndmask_b32_e64 v153, v153, v157, s[4:5]
	v_mul_f32_e32 v156, 0x37800000, v153
	v_cndmask_b32_e64 v153, v153, v156, s[2:3]
	v_cmp_class_f32_e64 s[2:3], v152, v119
	s_waitcnt vmcnt(23)
	v_and_b32_e32 v157, 0xffff0000, v136
	v_cndmask_b32_e64 v152, v153, v152, s[2:3]
	v_div_scale_f32 v153, s[2:3], v152, v152, 1.0
	v_rcp_f32_e32 v156, v153
	s_nop 0
	v_fma_f32 v102, -v153, v156, 1.0
	v_fmac_f32_e32 v156, v102, v156
	v_div_scale_f32 v102, vcc, 1.0, v152, 1.0
	v_mul_f32_e32 v154, v102, v156
	v_fma_f32 v155, -v153, v154, v102
	v_fmac_f32_e32 v154, v155, v156
	v_fma_f32 v102, -v153, v154, v102
	v_div_fmas_f32 v102, v102, v156, v154
	v_lshlrev_b32_e32 v156, 16, v136
	v_lshlrev_b32_e32 v136, 16, v137
	v_and_b32_e32 v137, 0xffff0000, v137
	v_pk_mul_f32 v[156:157], v[104:105], v[156:157] op_sel_hi:[0,1]
	v_pk_mul_f32 v[136:137], v[104:105], v[136:137] op_sel_hi:[0,1]
	v_div_fixup_f32 v102, v102, v152, 1.0
	v_lshl_add_u64 v[152:153], s[10:11], 0, v[80:81]
	v_pk_fma_f32 v[120:121], v[28:29], v[156:157], v[120:121]
	v_pk_fma_f32 v[122:123], v[30:31], v[136:137], v[122:123]
	global_store_dwordx4 v[152:153], v[120:123], off nt
	v_lshl_add_u64 v[154:155], v[88:89], 0, s[20:21]
	s_add_u32 s10, s10, s12
	s_waitcnt vmcnt(20)
	v_lshlrev_b32_e32 v120, 16, v142
	v_and_b32_e32 v121, 0xffff0000, v142
	v_lshlrev_b32_e32 v122, 16, v143
	v_and_b32_e32 v123, 0xffff0000, v143
	v_pk_mul_f32 v[120:121], v[102:103], v[120:121] op_sel_hi:[0,1]
	v_pk_mul_f32 v[122:123], v[102:103], v[122:123] op_sel_hi:[0,1]
	v_pk_fma_f32 v[120:121], v[28:29], v[120:121], v[128:129]
	v_pk_fma_f32 v[122:123], v[30:31], v[122:123], v[130:131]
	global_store_dwordx4 v[154:155], v[120:123], off nt
	s_addc_u32 s11, s11, s13
	s_add_u32 s16, s16, s12
	v_lshlrev_b32_e32 v120, 16, v138
	v_and_b32_e32 v121, 0xffff0000, v138
	v_lshlrev_b32_e32 v122, 16, v139
	v_and_b32_e32 v123, 0xffff0000, v139
	v_pk_mul_f32 v[120:121], v[104:105], v[120:121] op_sel_hi:[0,1]
	v_pk_mul_f32 v[122:123], v[104:105], v[122:123] op_sel_hi:[0,1]
	v_pk_fma_f32 v[120:121], v[24:25], v[120:121], v[124:125]
	v_pk_fma_f32 v[122:123], v[26:27], v[122:123], v[126:127]
	global_store_dwordx4 v[152:153], v[120:123], off offset:1024 nt
	s_addc_u32 s17, s17, s13
	s_cmpk_lt_i32 s6, 0x4000
	s_waitcnt vmcnt(21)
	v_lshlrev_b32_e32 v120, 16, v144
	v_and_b32_e32 v121, 0xffff0000, v144
	v_lshlrev_b32_e32 v122, 16, v145
	v_and_b32_e32 v123, 0xffff0000, v145
	v_pk_mul_f32 v[120:121], v[102:103], v[120:121] op_sel_hi:[0,1]
	v_pk_mul_f32 v[122:123], v[102:103], v[122:123] op_sel_hi:[0,1]
	v_pk_fma_f32 v[120:121], v[24:25], v[120:121], v[132:133]
	v_pk_fma_f32 v[122:123], v[26:27], v[122:123], v[134:135]
	global_store_dwordx4 v[154:155], v[120:123], off offset:1024 nt
	s_nop 1
	v_lshlrev_b32_e32 v120, 16, v140
	v_and_b32_e32 v121, 0xffff0000, v140
	v_pk_mul_f32 v[120:121], v[104:105], v[120:121] op_sel_hi:[0,1]
	v_pk_fma_f32 v[76:77], v[20:21], v[120:121], v[76:77]
	v_lshlrev_b32_e32 v120, 16, v141
	v_and_b32_e32 v121, 0xffff0000, v141
	v_pk_mul_f32 v[120:121], v[104:105], v[120:121] op_sel_hi:[0,1]
	v_pk_fma_f32 v[78:79], v[22:23], v[120:121], v[78:79]
	global_store_dwordx4 v[152:153], v[76:79], off offset:2048 nt
	s_waitcnt vmcnt(22)
	s_nop 0
	v_lshlrev_b32_e32 v76, 16, v146
	v_and_b32_e32 v77, 0xffff0000, v146
	v_pk_mul_f32 v[76:77], v[102:103], v[76:77] op_sel_hi:[0,1]
	v_pk_fma_f32 v[72:73], v[20:21], v[76:77], v[72:73]
	v_lshlrev_b32_e32 v76, 16, v147
	v_and_b32_e32 v77, 0xffff0000, v147
	v_pk_mul_f32 v[76:77], v[102:103], v[76:77] op_sel_hi:[0,1]
	v_pk_fma_f32 v[74:75], v[22:23], v[76:77], v[74:75]
	global_store_dwordx4 v[154:155], v[72:75], off offset:2048 nt
	s_nop 1
	v_lshlrev_b32_e32 v72, 16, v110
	v_and_b32_e32 v73, 0xffff0000, v110
	v_pk_mul_f32 v[72:73], v[104:105], v[72:73] op_sel_hi:[0,1]
	v_pk_fma_f32 v[60:61], v[16:17], v[72:73], v[60:61]
	v_lshlrev_b32_e32 v72, 16, v111
	v_and_b32_e32 v73, 0xffff0000, v111
	v_pk_mul_f32 v[72:73], v[104:105], v[72:73] op_sel_hi:[0,1]
	v_pk_fma_f32 v[62:63], v[18:19], v[72:73], v[62:63]
	global_store_dwordx4 v[152:153], v[60:63], off offset:3072 nt
	s_waitcnt vmcnt(23)
	s_nop 0
	v_lshlrev_b32_e32 v60, 16, v112
	v_and_b32_e32 v61, 0xffff0000, v112
	v_pk_mul_f32 v[60:61], v[102:103], v[60:61] op_sel_hi:[0,1]
	v_pk_fma_f32 v[56:57], v[16:17], v[60:61], v[56:57]
	v_lshlrev_b32_e32 v60, 16, v113
	v_and_b32_e32 v61, 0xffff0000, v113
	v_pk_mul_f32 v[60:61], v[102:103], v[60:61] op_sel_hi:[0,1]
	v_pk_fma_f32 v[58:59], v[18:19], v[60:61], v[58:59]
	global_store_dwordx4 v[154:155], v[56:59], off offset:3072 nt
	v_add_co_u32_e32 v60, vcc, s23, v152
	s_waitcnt vmcnt(15)
	v_lshlrev_b32_e32 v56, 16, v148
	v_and_b32_e32 v57, 0xffff0000, v148
	v_lshlrev_b32_e32 v58, 16, v149
	v_and_b32_e32 v59, 0xffff0000, v149
	v_pk_mul_f32 v[56:57], v[104:105], v[56:57] op_sel_hi:[0,1]
	v_pk_mul_f32 v[58:59], v[104:105], v[58:59] op_sel_hi:[0,1]
	v_pk_fma_f32 v[56:57], v[12:13], v[56:57], v[68:69]
	v_pk_fma_f32 v[58:59], v[14:15], v[58:59], v[70:71]
	v_addc_co_u32_e32 v61, vcc, 0, v153, vcc
	global_store_dwordx4 v[60:61], v[56:59], off nt
	v_add_co_u32_e32 v62, vcc, s23, v154
	s_waitcnt vmcnt(12)
	v_lshlrev_b32_e32 v56, 16, v150
	v_and_b32_e32 v57, 0xffff0000, v150
	v_lshlrev_b32_e32 v58, 16, v151
	v_and_b32_e32 v59, 0xffff0000, v151
	v_pk_mul_f32 v[56:57], v[102:103], v[56:57] op_sel_hi:[0,1]
	v_pk_mul_f32 v[58:59], v[102:103], v[58:59] op_sel_hi:[0,1]
	v_pk_fma_f32 v[56:57], v[12:13], v[56:57], v[64:65]
	v_pk_fma_f32 v[58:59], v[14:15], v[58:59], v[66:67]
	v_addc_co_u32_e32 v63, vcc, 0, v155, vcc
	global_store_dwordx4 v[62:63], v[56:59], off nt
	s_nop 1
	v_lshlrev_b32_e32 v56, 16, v106
	v_and_b32_e32 v57, 0xffff0000, v106
	v_pk_mul_f32 v[56:57], v[104:105], v[56:57] op_sel_hi:[0,1]
	v_pk_fma_f32 v[52:53], v[8:9], v[56:57], v[52:53]
	v_lshlrev_b32_e32 v56, 16, v107
	v_and_b32_e32 v57, 0xffff0000, v107
	v_pk_mul_f32 v[56:57], v[104:105], v[56:57] op_sel_hi:[0,1]
	v_pk_fma_f32 v[54:55], v[10:11], v[56:57], v[54:55]
	global_store_dwordx4 v[60:61], v[52:55], off offset:1024 nt
	s_waitcnt vmcnt(13)
	s_nop 0
	v_lshlrev_b32_e32 v52, 16, v108
	v_and_b32_e32 v53, 0xffff0000, v108
	v_pk_mul_f32 v[52:53], v[102:103], v[52:53] op_sel_hi:[0,1]
	v_pk_fma_f32 v[48:49], v[8:9], v[52:53], v[48:49]
	v_lshlrev_b32_e32 v52, 16, v109
	v_and_b32_e32 v53, 0xffff0000, v109
	v_pk_mul_f32 v[52:53], v[102:103], v[52:53] op_sel_hi:[0,1]
	v_pk_fma_f32 v[50:51], v[10:11], v[52:53], v[50:51]
	global_store_dwordx4 v[62:63], v[48:51], off offset:1024 nt
	s_nop 1
	v_lshlrev_b32_e32 v48, 16, v98
	v_and_b32_e32 v49, 0xffff0000, v98
	v_pk_mul_f32 v[48:49], v[104:105], v[48:49] op_sel_hi:[0,1]
	v_pk_fma_f32 v[44:45], v[4:5], v[48:49], v[44:45]
	v_lshlrev_b32_e32 v48, 16, v99
	v_and_b32_e32 v49, 0xffff0000, v99
	v_pk_mul_f32 v[48:49], v[104:105], v[48:49] op_sel_hi:[0,1]
	v_pk_fma_f32 v[46:47], v[6:7], v[48:49], v[46:47]
	global_store_dwordx4 v[60:61], v[44:47], off offset:2048 nt
	s_waitcnt vmcnt(14)
	s_nop 0
	v_lshlrev_b32_e32 v44, 16, v100
	v_and_b32_e32 v45, 0xffff0000, v100
	v_pk_mul_f32 v[44:45], v[102:103], v[44:45] op_sel_hi:[0,1]
	v_pk_fma_f32 v[40:41], v[4:5], v[44:45], v[40:41]
	v_lshlrev_b32_e32 v44, 16, v101
	v_and_b32_e32 v45, 0xffff0000, v101
	v_pk_mul_f32 v[44:45], v[102:103], v[44:45] op_sel_hi:[0,1]
	v_pk_fma_f32 v[42:43], v[6:7], v[44:45], v[42:43]
	global_store_dwordx4 v[62:63], v[40:43], off offset:2048 nt
	s_nop 1
	v_lshlrev_b32_e32 v40, 16, v94
	v_and_b32_e32 v41, 0xffff0000, v94
	v_pk_mul_f32 v[40:41], v[104:105], v[40:41] op_sel_hi:[0,1]
	v_pk_fma_f32 v[36:37], v[0:1], v[40:41], v[36:37]
	v_lshlrev_b32_e32 v40, 16, v95
	v_and_b32_e32 v41, 0xffff0000, v95
	v_pk_mul_f32 v[40:41], v[104:105], v[40:41] op_sel_hi:[0,1]
	v_pk_fma_f32 v[38:39], v[2:3], v[40:41], v[38:39]
	global_store_dwordx4 v[60:61], v[36:39], off offset:3072 nt
	s_waitcnt vmcnt(15)
	s_nop 0
	v_lshlrev_b32_e32 v36, 16, v96
	v_and_b32_e32 v37, 0xffff0000, v96
	v_pk_mul_f32 v[36:37], v[102:103], v[36:37] op_sel_hi:[0,1]
	v_pk_fma_f32 v[32:33], v[0:1], v[36:37], v[32:33]
	v_lshlrev_b32_e32 v36, 16, v97
	v_and_b32_e32 v37, 0xffff0000, v97
	v_pk_mul_f32 v[36:37], v[102:103], v[36:37] op_sel_hi:[0,1]
	v_pk_fma_f32 v[34:35], v[2:3], v[36:37], v[34:35]
	global_store_dwordx4 v[62:63], v[32:35], off offset:3072 nt
	s_cbranch_scc0 .LBB0_757
